# scan consumer: (row0,row1)-packed state pairs (no horizontal adds), both steps' y reduced together via masked half-mirror DPP, one LDS store per 2 steps
# speedup vs baseline: 1.0113x; 1.0093x over previous
; __device__ __forceinline__ void scan_chain(const Params& p, int l, int chain, unsigned char* lds) {
;     ...
;             auto ld = [&](int s, StepIn& I) {
;                 const int ts = dir == 0 ? s : 31 - s; const float* ap = arr + ts * 64 + 8 * cgp;
;                 I.w0 = *(const f32x4*)(ap); I.w1 = *(const f32x4*)(ap + 4); I.k0 = *(const f32x4*)(ap + 2048); I.k1 = *(const f32x4*)(ap + 2048 + 4);
;                 I.a0 = *(const f32x4*)(ap + 4096); I.a1 = *(const f32x4*)(ap + 4096 + 4); I.b0 = *(const f32x4*)(ap + 6144); I.b1 = *(const f32x4*)(ap + 6144 + 4);
;                 I.r0 = *(const f32x4*)(ap + 8192); I.r1 = *(const f32x4*)(ap + 8192 + 4);
;                 I.v0 = arr[5 * 2048 + ts * 64 + i0]; I.v1 = arr[5 * 2048 + ts * 64 + i1];
;             };
;             auto comp = [&](int s, const StepIn& I) {
;                 const int ts = dir == 0 ? s : 31 - s;
;                 const f32x2 w[4] = {{I.w0[0], I.w0[1]}, {I.w0[2], I.w0[3]}, {I.w1[0], I.w1[1]}, {I.w1[2], I.w1[3]}};
;                 const f32x2 k[4] = {{I.k0[0], I.k0[1]}, {I.k0[2], I.k0[3]}, {I.k1[0], I.k1[1]}, {I.k1[2], I.k1[3]}};
;                 const f32x2 a[4] = {{I.a0[0], I.a0[1]}, {I.a0[2], I.a0[3]}, {I.a1[0], I.a1[1]}, {I.a1[2], I.a1[3]}};
;                 const f32x2 bb[4] = {{I.b0[0], I.b0[1]}, {I.b0[2], I.b0[3]}, {I.b1[0], I.b1[1]}, {I.b1[2], I.b1[3]}};
;                 const f32x2 r[4] = {{I.r0[0], I.r0[1]}, {I.r0[2], I.r0[3]}, {I.r1[0], I.r1[1]}, {I.r1[2], I.r1[3]}};
;                 f32x2 d0 = S0[0] * a[0] + S0[1] * a[1], d0b = S0[2] * a[2] + S0[3] * a[3];
;                 f32x2 d1 = S1[0] * a[0] + S1[1] * a[1], d1b = S1[2] * a[2] + S1[3] * a[3];
;                 d0 += d0b; d1 += d1b;
;                 const float sa0 = sum8(d0.x + d0.y), sa1 = sum8(d1.x + d1.y);
; #pragma unroll
;                 for (int e = 0; e < 4; ++e) { S0[e] = S0[e] * w[e] + bb[e] * sa0 + k[e] * I.v0; S1[e] = S1[e] * w[e] + bb[e] * sa1 + k[e] * I.v1; }
;                 f32x2 y0 = S0[0] * r[0] + S0[1] * r[1], y0b = S0[2] * r[2] + S0[3] * r[3];
;                 f32x2 y1 = S1[0] * r[0] + S1[1] * r[1], y1b = S1[2] * r[2] + S1[3] * r[3];
;                 y0 += y0b; y1 += y1b;
;                 const float ya = sum8(y0.x + y0.y), yb = sum8(y1.x + y1.y);
;                 if (cgp == 0) { yl[ts * 64 + i0] = ya; yl[ts * 64 + i1] = yb; }
;             };
;             __builtin_amdgcn_s_setprio(3);
.LBB0_316:
	s_andn2_b64 vcc, exec, s[0:1]
	s_cbranch_vccnz .LBB0_326
	s_and_b32 s0, s10, 1
	s_mul_i32 s1, s0, 0xc000
	s_lshl_b32 s0, s0, 13
	s_add_i32 s0, s0, 0
	s_add_i32 s1, s1, 0
	s_add_i32 s0, s0, 0x18000
	s_setprio 3
	v_readlane_b32 s6, v253, 37
	s_add_i32 s2, s1, s6
	v_add_u32_e32 v0, s2, v229
	ds_read_b128 v[2:5], v0
	ds_read_b128 v[6:9], v0 offset:16
	ds_read_b128 v[10:13], v0 offset:8192
	ds_read_b128 v[14:17], v0 offset:8208
	s_waitcnt vmcnt(14)
	ds_read_b128 v[78:81], v0 offset:16384
	s_waitcnt vmcnt(13)
	ds_read_b128 v[82:85], v0 offset:16400
	s_waitcnt vmcnt(12)
	ds_read_b128 v[86:89], v0 offset:24576
	s_waitcnt vmcnt(11)
	ds_read_b128 v[90:93], v0 offset:24592
	s_waitcnt vmcnt(10)
	ds_read_b128 v[94:97], v0 offset:32768
	s_waitcnt vmcnt(9)
	ds_read_b128 v[98:101], v0 offset:32784
	v_add_u32_e32 v162, s1, v247
	v_add_u32_e32 v0, s6, v162
	v_add_u32_e32 v0, 0xa000, v0
	ds_read2_b32 v[142:143], v0 offset1:8
	v_add_u32_e32 v163, s1, v229
	v_add_u32_e32 v164, s0, v247
	s_movk_i32 s12, 0x100
	s_movk_i32 s13, 0xff00
	s_and_b64 s[0:1], s[68:69], exec
	s_cselect_b32 s7, s12, s13
	s_add_i32 s12, s6, s7
	s_add_i32 s13, s12, 0xa000
	v_add_u32_e32 v18, s12, v163
	v_add_u32_e32 v19, s13, v162
	v_bfe_u32 v165, v229, 7, 1
	v_mul_lo_u32 v165, v165, s7
	s_lshl_b64 s[14:15], s[42:43], 4
	v_add3_u32 v20, v164, s6, v165
	s_or_b64 s[14:15], s[14:15], s[42:43]
	s_lshl_b32 s12, s7, 1
	s_movk_i32 s2, 16
	s_waitcnt lgkmcnt(0)
.Lscan_iter:
	s_cmp_eq_u32 s2, 1
	s_cselect_b32 s13, 0, s7
	s_waitcnt lgkmcnt(1)
	v_pk_mul_f32 v[166:167], v[210:211], v[78:79] op_sel_hi:[1,0]
	ds_read_b128 v[118:121], v18 offset:16384
	v_pk_fma_f32 v[166:167], v[212:213], v[78:79], v[166:167] op_sel:[0,1,0]
	ds_read_b128 v[122:125], v18 offset:16400
	ds_read_b128 v[110:113], v18 offset:8192
	v_pk_fma_f32 v[166:167], v[214:215], v[80:81], v[166:167] op_sel_hi:[1,0,1]
	ds_read_b128 v[114:117], v18 offset:8208
	v_pk_fma_f32 v[166:167], v[216:217], v[80:81], v[166:167] op_sel:[0,1,0]
	ds_read2_b32 v[144:145], v19 offset1:8
	ds_read_b128 v[102:105], v18
	v_pk_fma_f32 v[166:167], v[218:219], v[82:83], v[166:167] op_sel_hi:[1,0,1]
	ds_read_b128 v[106:109], v18 offset:16
	v_pk_fma_f32 v[166:167], v[220:221], v[82:83], v[166:167] op_sel:[0,1,0]
	ds_read_b128 v[126:129], v18 offset:24576
	ds_read_b128 v[130:133], v18 offset:24592
	v_pk_fma_f32 v[166:167], v[222:223], v[84:85], v[166:167] op_sel_hi:[1,0,1]
	ds_read_b128 v[134:137], v18 offset:32768
	v_pk_fma_f32 v[166:167], v[224:225], v[84:85], v[166:167] op_sel:[0,1,0]
	ds_read_b128 v[138:141], v18 offset:32784
	v_pk_mul_f32 v[146:147], v[10:11], v[142:143] op_sel_hi:[0,1]
	v_pk_mul_f32 v[148:149], v[10:11], v[142:143] op_sel:[1,0]
	v_add_f32_dpp v166, v166, v166 quad_perm:[1,0,3,2] row_mask:0xf bank_mask:0xf bound_ctrl:1
	v_add_f32_dpp v167, v167, v167 quad_perm:[1,0,3,2] row_mask:0xf bank_mask:0xf bound_ctrl:1
	v_pk_mul_f32 v[150:151], v[12:13], v[142:143] op_sel_hi:[0,1]
	v_pk_mul_f32 v[152:153], v[12:13], v[142:143] op_sel:[1,0]
	v_pk_mul_f32 v[154:155], v[14:15], v[142:143] op_sel_hi:[0,1]
	v_add_f32_dpp v166, v166, v166 quad_perm:[2,3,0,1] row_mask:0xf bank_mask:0xf bound_ctrl:1
	v_add_f32_dpp v167, v167, v167 quad_perm:[2,3,0,1] row_mask:0xf bank_mask:0xf bound_ctrl:1
	v_pk_mul_f32 v[156:157], v[14:15], v[142:143] op_sel:[1,0]
	v_pk_mul_f32 v[158:159], v[16:17], v[142:143] op_sel_hi:[0,1]
	v_pk_mul_f32 v[160:161], v[16:17], v[142:143] op_sel:[1,0]
	v_add_f32_dpp v166, v166, v166 row_half_mirror row_mask:0xf bank_mask:0xf bound_ctrl:1
	v_add_f32_dpp v167, v167, v167 row_half_mirror row_mask:0xf bank_mask:0xf bound_ctrl:1
	v_pk_fma_f32 v[146:147], v[210:211], v[2:3], v[146:147] op_sel_hi:[1,0,1]
	v_pk_fma_f32 v[148:149], v[212:213], v[2:3], v[148:149] op_sel:[0,1,0]
	v_pk_fma_f32 v[150:151], v[214:215], v[4:5], v[150:151] op_sel_hi:[1,0,1]
	v_pk_fma_f32 v[152:153], v[216:217], v[4:5], v[152:153] op_sel:[0,1,0]
	v_pk_fma_f32 v[154:155], v[218:219], v[6:7], v[154:155] op_sel_hi:[1,0,1]
	v_pk_fma_f32 v[156:157], v[220:221], v[6:7], v[156:157] op_sel:[0,1,0]
	v_pk_fma_f32 v[158:159], v[222:223], v[8:9], v[158:159] op_sel_hi:[1,0,1]
	v_pk_fma_f32 v[160:161], v[224:225], v[8:9], v[160:161] op_sel:[0,1,0]
	v_pk_fma_f32 v[146:147], v[86:87], v[166:167], v[146:147] op_sel_hi:[0,1,1]
	v_pk_fma_f32 v[148:149], v[86:87], v[166:167], v[148:149] op_sel:[1,0,0]
	v_pk_mul_f32 v[170:171], v[146:147], v[94:95] op_sel_hi:[1,0]
	v_pk_fma_f32 v[150:151], v[88:89], v[166:167], v[150:151] op_sel_hi:[0,1,1]
	v_pk_fma_f32 v[170:171], v[148:149], v[94:95], v[170:171] op_sel:[0,1,0]
	v_pk_fma_f32 v[152:153], v[88:89], v[166:167], v[152:153] op_sel:[1,0,0]
	v_pk_fma_f32 v[170:171], v[150:151], v[96:97], v[170:171] op_sel_hi:[1,0,1]
	v_pk_fma_f32 v[154:155], v[90:91], v[166:167], v[154:155] op_sel_hi:[0,1,1]
	v_pk_fma_f32 v[170:171], v[152:153], v[96:97], v[170:171] op_sel:[0,1,0]
	v_pk_fma_f32 v[156:157], v[90:91], v[166:167], v[156:157] op_sel:[1,0,0]
	v_pk_fma_f32 v[170:171], v[154:155], v[98:99], v[170:171] op_sel_hi:[1,0,1]
	v_pk_fma_f32 v[158:159], v[92:93], v[166:167], v[158:159] op_sel_hi:[0,1,1]
	v_pk_fma_f32 v[170:171], v[156:157], v[98:99], v[170:171] op_sel:[0,1,0]
	v_pk_fma_f32 v[160:161], v[92:93], v[166:167], v[160:161] op_sel:[1,0,0]
	v_pk_fma_f32 v[170:171], v[158:159], v[100:101], v[170:171] op_sel_hi:[1,0,1]
	v_add_u32_e32 v18, s13, v18
	v_add_u32_e32 v19, s13, v19
	v_pk_fma_f32 v[170:171], v[160:161], v[100:101], v[170:171] op_sel:[0,1,0]
	s_waitcnt lgkmcnt(0)
; __device__ __forceinline__ float sum8(float v) { v += dpp_xor1(v); v += dpp_xor2(v); v += dpp_hmir(v); return v; }
; __device__ __forceinline__ void scan_chain(const Params& p, int l, int chain, unsigned char* lds) {
;     ...
;             auto comp = [&](int s, const StepIn& I) {
;                 const int ts = dir == 0 ? s : 31 - s;
;                 const f32x2 w[4] = {{I.w0[0], I.w0[1]}, {I.w0[2], I.w0[3]}, {I.w1[0], I.w1[1]}, {I.w1[2], I.w1[3]}};
;                 const f32x2 k[4] = {{I.k0[0], I.k0[1]}, {I.k0[2], I.k0[3]}, {I.k1[0], I.k1[1]}, {I.k1[2], I.k1[3]}};
;                 const f32x2 a[4] = {{I.a0[0], I.a0[1]}, {I.a0[2], I.a0[3]}, {I.a1[0], I.a1[1]}, {I.a1[2], I.a1[3]}};
;                 const f32x2 bb[4] = {{I.b0[0], I.b0[1]}, {I.b0[2], I.b0[3]}, {I.b1[0], I.b1[1]}, {I.b1[2], I.b1[3]}};
;                 const f32x2 r[4] = {{I.r0[0], I.r0[1]}, {I.r0[2], I.r0[3]}, {I.r1[0], I.r1[1]}, {I.r1[2], I.r1[3]}};
;                 f32x2 d0 = S0[0] * a[0] + S0[1] * a[1], d0b = S0[2] * a[2] + S0[3] * a[3];
;                 f32x2 d1 = S1[0] * a[0] + S1[1] * a[1], d1b = S1[2] * a[2] + S1[3] * a[3];
;                 d0 += d0b; d1 += d1b;
;                 const float sa0 = sum8(d0.x + d0.y), sa1 = sum8(d1.x + d1.y);
; #pragma unroll
;                 for (int e = 0; e < 4; ++e) { S0[e] = S0[e] * w[e] + bb[e] * sa0 + k[e] * I.v0; S1[e] = S1[e] * w[e] + bb[e] * sa1 + k[e] * I.v1; }
;                 f32x2 y0 = S0[0] * r[0] + S0[1] * r[1], y0b = S0[2] * r[2] + S0[3] * r[3];
;                 f32x2 y1 = S1[0] * r[0] + S1[1] * r[1], y1b = S1[2] * r[2] + S1[3] * r[3];
;                 y0 += y0b; y1 += y1b;
;                 const float ya = sum8(y0.x + y0.y), yb = sum8(y1.x + y1.y);
;                 if (cgp == 0) { yl[ts * 64 + i0] = ya; yl[ts * 64 + i1] = yb; }
;             };
;             __builtin_amdgcn_s_setprio(3);
;             StepIn IA, IB;
;             ld(0, IA);
; #pragma unroll 1
;             for (int s = 0; s < 32; s += 2) {
;                 ld(s + 1, IB);
;                 comp(s, IA);
;                 if (s + 2 < 32) ld(s + 2, IA);
;                 comp(s + 1, IB);
;             }
	v_pk_mul_f32 v[166:167], v[146:147], v[118:119] op_sel_hi:[1,0]
	ds_read_b128 v[78:81], v18 offset:16384
	v_pk_fma_f32 v[166:167], v[148:149], v[118:119], v[166:167] op_sel:[0,1,0]
	ds_read_b128 v[82:85], v18 offset:16400
	ds_read_b128 v[10:13], v18 offset:8192
	v_pk_fma_f32 v[166:167], v[150:151], v[120:121], v[166:167] op_sel_hi:[1,0,1]
	ds_read_b128 v[14:17], v18 offset:8208
	v_pk_fma_f32 v[166:167], v[152:153], v[120:121], v[166:167] op_sel:[0,1,0]
	ds_read2_b32 v[142:143], v19 offset1:8
	ds_read_b128 v[2:5], v18
	v_pk_fma_f32 v[166:167], v[154:155], v[122:123], v[166:167] op_sel_hi:[1,0,1]
	ds_read_b128 v[6:9], v18 offset:16
	v_pk_fma_f32 v[166:167], v[156:157], v[122:123], v[166:167] op_sel:[0,1,0]
	ds_read_b128 v[86:89], v18 offset:24576
	ds_read_b128 v[90:93], v18 offset:24592
	v_pk_fma_f32 v[166:167], v[158:159], v[124:125], v[166:167] op_sel_hi:[1,0,1]
	ds_read_b128 v[94:97], v18 offset:32768
	v_pk_fma_f32 v[166:167], v[160:161], v[124:125], v[166:167] op_sel:[0,1,0]
	ds_read_b128 v[98:101], v18 offset:32784
	v_pk_mul_f32 v[210:211], v[110:111], v[144:145] op_sel_hi:[0,1]
	v_pk_mul_f32 v[212:213], v[110:111], v[144:145] op_sel:[1,0]
	v_add_f32_dpp v166, v166, v166 quad_perm:[1,0,3,2] row_mask:0xf bank_mask:0xf bound_ctrl:1
	v_add_f32_dpp v167, v167, v167 quad_perm:[1,0,3,2] row_mask:0xf bank_mask:0xf bound_ctrl:1
	v_pk_mul_f32 v[214:215], v[112:113], v[144:145] op_sel_hi:[0,1]
	v_pk_mul_f32 v[216:217], v[112:113], v[144:145] op_sel:[1,0]
	v_pk_mul_f32 v[218:219], v[114:115], v[144:145] op_sel_hi:[0,1]
	v_add_f32_dpp v166, v166, v166 quad_perm:[2,3,0,1] row_mask:0xf bank_mask:0xf bound_ctrl:1
	v_add_f32_dpp v167, v167, v167 quad_perm:[2,3,0,1] row_mask:0xf bank_mask:0xf bound_ctrl:1
	v_pk_mul_f32 v[220:221], v[114:115], v[144:145] op_sel:[1,0]
	v_pk_mul_f32 v[222:223], v[116:117], v[144:145] op_sel_hi:[0,1]
	v_pk_mul_f32 v[224:225], v[116:117], v[144:145] op_sel:[1,0]
	v_add_f32_dpp v166, v166, v166 row_half_mirror row_mask:0xf bank_mask:0xf bound_ctrl:1
	v_add_f32_dpp v167, v167, v167 row_half_mirror row_mask:0xf bank_mask:0xf bound_ctrl:1
	v_pk_fma_f32 v[210:211], v[146:147], v[102:103], v[210:211] op_sel_hi:[1,0,1]
	v_pk_fma_f32 v[212:213], v[148:149], v[102:103], v[212:213] op_sel:[0,1,0]
	v_pk_fma_f32 v[214:215], v[150:151], v[104:105], v[214:215] op_sel_hi:[1,0,1]
	v_pk_fma_f32 v[216:217], v[152:153], v[104:105], v[216:217] op_sel:[0,1,0]
	v_pk_fma_f32 v[218:219], v[154:155], v[106:107], v[218:219] op_sel_hi:[1,0,1]
	v_pk_fma_f32 v[220:221], v[156:157], v[106:107], v[220:221] op_sel:[0,1,0]
	v_pk_fma_f32 v[222:223], v[158:159], v[108:109], v[222:223] op_sel_hi:[1,0,1]
	v_pk_fma_f32 v[224:225], v[160:161], v[108:109], v[224:225] op_sel:[0,1,0]
	v_pk_fma_f32 v[210:211], v[126:127], v[166:167], v[210:211] op_sel_hi:[0,1,1]
	v_pk_fma_f32 v[212:213], v[126:127], v[166:167], v[212:213] op_sel:[1,0,0]
	v_pk_mul_f32 v[172:173], v[210:211], v[134:135] op_sel_hi:[1,0]
	v_pk_fma_f32 v[214:215], v[128:129], v[166:167], v[214:215] op_sel_hi:[0,1,1]
	v_pk_fma_f32 v[172:173], v[212:213], v[134:135], v[172:173] op_sel:[0,1,0]
	v_pk_fma_f32 v[216:217], v[128:129], v[166:167], v[216:217] op_sel:[1,0,0]
	v_pk_fma_f32 v[172:173], v[214:215], v[136:137], v[172:173] op_sel_hi:[1,0,1]
	v_pk_fma_f32 v[218:219], v[130:131], v[166:167], v[218:219] op_sel_hi:[0,1,1]
	v_pk_fma_f32 v[172:173], v[216:217], v[136:137], v[172:173] op_sel:[0,1,0]
	v_pk_fma_f32 v[220:221], v[130:131], v[166:167], v[220:221] op_sel:[1,0,0]
	v_pk_fma_f32 v[172:173], v[218:219], v[138:139], v[172:173] op_sel_hi:[1,0,1]
	v_pk_fma_f32 v[222:223], v[132:133], v[166:167], v[222:223] op_sel_hi:[0,1,1]
	v_pk_fma_f32 v[172:173], v[220:221], v[138:139], v[172:173] op_sel:[0,1,0]
	v_pk_fma_f32 v[224:225], v[132:133], v[166:167], v[224:225] op_sel:[1,0,0]
	v_pk_fma_f32 v[172:173], v[222:223], v[140:141], v[172:173] op_sel_hi:[1,0,1]
	v_pk_fma_f32 v[172:173], v[224:225], v[140:141], v[172:173] op_sel:[0,1,0]
	v_add_f32_dpp v168, v170, v170 row_half_mirror row_mask:0xf bank_mask:0x5 bound_ctrl:1
	v_add_f32_dpp v169, v171, v171 row_half_mirror row_mask:0xf bank_mask:0x5 bound_ctrl:1
	v_add_f32_dpp v168, v172, v172 row_half_mirror row_mask:0xf bank_mask:0xa bound_ctrl:1
	v_add_f32_dpp v169, v173, v173 row_half_mirror row_mask:0xf bank_mask:0xa bound_ctrl:1
	v_add_u32_e32 v18, s7, v18
	v_add_f32_dpp v168, v168, v168 quad_perm:[1,0,3,2] row_mask:0xf bank_mask:0xf bound_ctrl:1
	v_add_f32_dpp v169, v169, v169 quad_perm:[1,0,3,2] row_mask:0xf bank_mask:0xf bound_ctrl:1
	v_add_u32_e32 v19, s7, v19
	v_add_f32_dpp v168, v168, v168 quad_perm:[2,3,0,1] row_mask:0xf bank_mask:0xf bound_ctrl:1
	v_add_f32_dpp v169, v169, v169 quad_perm:[2,3,0,1] row_mask:0xf bank_mask:0xf bound_ctrl:1
	s_add_i32 s2, s2, -1
	s_cmp_lg_u32 s2, 0
	s_mov_b64 exec, s[14:15]
	ds_write2_b32 v20, v168, v169 offset1:8
	s_mov_b64 exec, -1
	v_add_u32_e32 v20, s12, v20
	s_cbranch_scc1 .Lscan_iter
	s_branch .LBB0_304
